# compress-1 GEMM K-loop: global loads two K-tiles ahead (second register set), unrolled x2
# speedup vs baseline: 1.0075x; 1.0064x over previous
; DEVI int opaque_tid(int wv) { int t; asm volatile("v_mbcnt_lo_u32_b32 %0, -1, 0\n\tv_mbcnt_hi_u32_b32 %0, -1, %0" : "=v"(t)); return wv * 64 + t; }
; template <bool ROWSS, class AD, class Epi>
; DEVI void gemm_tile(const AD& ad, const bf16_t* __restrict__ Bt, int K, int m0, int n0, const Epi& epi, unsigned char* lds, int wv) {
;   const int tid = opaque_tid(wv), lane = tid & 63, wave = tid >> 6;
;   const int idx = lane & 15, quad = lane >> 4;
;   const int wm = wave >> 1, wn = wave & 1;
;   const int lc = tid & 7, lr = tid >> 3;
;   const bf16_t* ap[4]; const bf16_t* bp[2];
; #pragma unroll
;   for (int i = 0; i < 4; ++i) ap[i] = ad.rowptr(m0 + lr + 64 * i) + lc * 8;
; #pragma unroll
;   for (int i = 0; i < 2; ++i) bp[i] = Bt + (size_t)(n0 + lr + 64 * i) * K + lc * 8;
;   const int aks = ad.kstride;
;   u32x4 ra[4], rb[2];
;   float ss[4] = {0.f, 0.f, 0.f, 0.f};
;   f32x4 acc[4][4];
; #pragma unroll
;   for (int i = 0; i < 4; ++i)
; #pragma unroll
;     for (int j = 0; j < 4; ++j) acc[i][j] = (f32x4){0.f, 0.f, 0.f, 0.f};
;   const int nk = K >> 6;
; #pragma unroll
;   for (int i = 0; i < 4; ++i) ra[i] = *(const u32x4*)(ap[i]);
; #pragma unroll
;   for (int i = 0; i < 2; ++i) rb[i] = *(const u32x4*)(bp[i]);
;   auto stage_write = [&](int s) {
;     unsigned char* A = lds + s * LDS_STAGE; unsigned char* B = A + LDS_A_BYTES;
; #pragma unroll
;     for (int i = 0; i < 4; ++i) *(u32x4*)(A + (lr + 64 * i) * LDS_ROW + lc * 16) = ra[i];
; #pragma unroll
;     for (int i = 0; i < 2; ++i) *(u32x4*)(B + (lr + 64 * i) * LDS_ROW + lc * 16) = rb[i];
;     if (ROWSS) {
; #pragma unroll
;       for (int i = 0; i < 4; ++i)
; #pragma unroll
;         for (int e = 0; e < 4; ++e) { unsigned w = ra[i][e]; float lo = __uint_as_float(w << 16), hi = __uint_as_float(w & 0xffff0000u); ss[i] += lo * lo + hi * hi; }
;     }
;   };
;   stage_write(0);
;   __syncthreads();
.LBB0_839:
	s_and_b32 s2, s0, 1
	s_cmp_eq_u32 s2, 0
	s_movk_i32 s1, 0x300
	v_readlane_b32 s12, v252, 40
	s_cselect_b32 s9, s1, 0x400
	v_readlane_b32 s14, v252, 42
	v_readlane_b32 s15, v252, 43
	s_add_u32 s6, s14, s9
	s_addc_u32 s7, s15, 0
	s_or_b32 s4, s2, s8
	s_lshl_b32 s1, s4, 19
	v_readlane_b32 s3, v252, 55
	s_add_u32 s10, s3, s1
	v_readlane_b32 s1, v252, 56
	s_addc_u32 s11, s1, 0
	s_lshl_b32 s0, s0, 7
	s_and_b32 s3, s0, 0xffffff00
	v_readlane_b32 s0, v252, 46
	v_mbcnt_lo_u32_b32 v18, -1, 0
	v_mbcnt_hi_u32_b32 v18, -1, v18
	v_mov_b32_e32 v3, v33
	s_movk_i32 s5, 0x7f
	v_add_u32_e32 v19, s0, v18
	v_ashrrev_i32_e32 v0, 3, v19
	v_lshlrev_b32_e32 v2, 7, v0
	v_and_b32_e32 v2, 0x80, v2
	v_add_u32_e32 v1, s3, v0
	v_lshl_add_u64 v[4:5], s[6:7], 0, v[2:3]
	v_lshlrev_b32_e32 v3, 4, v18
	v_and_b32_e32 v32, 0x70, v3
	v_bfe_u32 v3, v0, 1, 7
	v_add_u32_e32 v8, 64, v1
	v_lshlrev_b32_e32 v7, 4, v3
	v_cmp_ne_u32_e32 vcc, s5, v3
	v_bfe_u32 v9, v8, 1, 7
	v_lshlrev_b32_e32 v10, 4, v9
	v_cndmask_b32_e32 v3, v235, v7, vcc
	v_cmp_ne_u32_e32 vcc, s5, v9
	v_lshlrev_b32_e32 v6, 3, v1
	s_movk_i32 s7, 0xf800
	v_cndmask_b32_e32 v9, v235, v10, vcc
	v_add_u32_e32 v10, 0x80, v1
	v_bfe_u32 v11, v10, 1, 7
	v_lshlrev_b32_e32 v12, 4, v11
	v_cmp_ne_u32_e32 vcc, s5, v11
	v_add_u32_e32 v1, 0xc0, v1
	v_lshlrev_b32_e32 v8, 3, v8
	v_cndmask_b32_e32 v11, v235, v12, vcc
	v_bfe_u32 v12, v1, 1, 7
	v_lshlrev_b32_e32 v13, 4, v12
	v_cmp_ne_u32_e32 vcc, s5, v12
	v_lshlrev_b32_e32 v10, 3, v10
	v_lshlrev_b32_e32 v1, 3, v1
	v_cndmask_b32_e32 v12, v235, v13, vcc
	v_lshl_add_u64 v[4:5], v[4:5], 0, v[32:33]
	v_and_or_b32 v3, v6, s7, v3
	s_movk_i32 s6, 0x1200
	v_and_or_b32 v20, v8, s7, v9
	v_and_or_b32 v21, v10, s7, v11
	v_and_or_b32 v22, v1, s7, v12
	v_ashrrev_i32_e32 v1, 31, v0
	v_mad_i64_i32 v[6:7], s[0:1], v3, s6, v[4:5]
	v_mad_i64_i32 v[8:9], s[0:1], v20, s6, v[4:5]
	v_mad_i64_i32 v[10:11], s[0:1], v21, s6, v[4:5]
	v_mad_i64_i32 v[4:5], s[0:1], v22, s6, v[4:5]
	v_lshl_add_u64 v[12:13], s[10:11], 0, v[32:33]
	v_lshlrev_b64 v[14:15], 12, v[0:1]
	v_lshl_add_u64 v[12:13], v[12:13], 0, v[14:15]
	s_mov_b32 s0, 0x40000
	v_add_co_u32_e32 v16, vcc, s0, v12
	s_movk_i32 s7, 0x90
	s_nop 0
	v_addc_co_u32_e32 v17, vcc, 0, v13, vcc
	global_load_dwordx4 v[78:81], v[12:13], off
	global_load_dwordx4 v[82:85], v[16:17], off
	global_load_dwordx4 v[62:65], v[6:7], off
	global_load_dwordx4 v[66:69], v[8:9], off
	global_load_dwordx4 v[70:73], v[10:11], off
	global_load_dwordx4 v[74:77], v[4:5], off
	v_ashrrev_i32_e32 v1, 1, v19
	v_mul_lo_u32 v0, v0, s7
	v_and_b32_e32 v103, 0xffffffc0, v1
	v_add3_u32 v104, 0, v0, v32
	v_mad_i64_i32 v[0:1], s[0:1], v3, s6, 0
	v_mad_i64_i32 v[4:5], s[0:1], v20, s6, 0
	v_mad_i64_i32 v[6:7], s[0:1], v21, s6, 0
	v_mad_i64_i32 v[8:9], s[0:1], v22, s6, 0
	v_readlane_b32 s0, v254, 53
	s_add_i32 s92, s0, s2
	s_lshl_b64 s[0:1], s[92:93], 19
	s_add_u32 s0, s14, s0
	s_addc_u32 s1, s15, s1
	v_lshl_add_u64 v[90:91], s[0:1], 0, v[14:15]
	v_readlane_b32 s0, v254, 40
	s_add_u32 s0, s0, s9
	v_readlane_b32 s1, v254, 41
	v_and_b32_e32 v101, 15, v18
	v_and_b32_e32 v102, 64, v19
	v_or_b32_e32 v0, v0, v2
	s_addc_u32 s1, s1, 0
	v_bfe_u32 v100, v18, 4, 2
	v_or_b32_e32 v10, v103, v101
	v_or_b32_e32 v3, v102, v101
	v_lshl_add_u64 v[92:93], s[0:1], 0, v[0:1]
	v_or_b32_e32 v4, v4, v2
	v_or_b32_e32 v6, v6, v2
	v_or_b32_e32 v8, v8, v2
	v_mov_b32_e32 v0, 0
	s_mov_b32 s5, 0
	s_movk_i32 s33, 0x1200
	v_mul_lo_u32 v105, v10, s7
	v_lshlrev_b32_e32 v106, 4, v100
	v_mul_u32_u24_e32 v107, 0x90, v3
	v_lshl_add_u64 v[94:95], s[0:1], 0, v[4:5]
	v_lshl_add_u64 v[96:97], s[0:1], 0, v[6:7]
	v_lshl_add_u64 v[98:99], s[0:1], 0, v[8:9]
	v_mov_b32_e32 v1, v0
	v_mov_b32_e32 v2, v0
	v_mov_b32_e32 v3, v0
	v_mov_b32_e32 v16, v0
	v_mov_b32_e32 v17, v0
	v_mov_b32_e32 v18, v0
	v_mov_b32_e32 v19, v0
	s_waitcnt vmcnt(14)
	v_mov_b32_e32 v34, v0
	v_mov_b32_e32 v35, v0
	v_mov_b32_e32 v36, v0
	v_mov_b32_e32 v37, v0
	v_mov_b32_e32 v50, v0
	v_mov_b32_e32 v51, v0
	v_mov_b32_e32 v52, v0
	v_mov_b32_e32 v53, v0
	v_mov_b32_e32 v4, v0
	v_mov_b32_e32 v5, v0
	v_mov_b32_e32 v6, v0
	v_mov_b32_e32 v7, v0
	v_mov_b32_e32 v20, v0
	v_mov_b32_e32 v21, v0
	v_mov_b32_e32 v22, v0
	v_mov_b32_e32 v23, v0
	v_mov_b32_e32 v38, v0
	v_mov_b32_e32 v39, v0
	v_mov_b32_e32 v40, v0
	v_mov_b32_e32 v41, v0
	v_mov_b32_e32 v54, v0
	v_mov_b32_e32 v55, v0
	v_mov_b32_e32 v56, v0
	v_mov_b32_e32 v57, v0
	v_mov_b32_e32 v8, v0
	v_mov_b32_e32 v9, v0
	v_mov_b32_e32 v10, v0
	v_mov_b32_e32 v11, v0
	v_mov_b32_e32 v24, v0
	v_mov_b32_e32 v25, v0
	v_mov_b32_e32 v26, v0
	v_mov_b32_e32 v27, v0
	v_mov_b32_e32 v42, v0
	v_mov_b32_e32 v43, v0
	v_mov_b32_e32 v44, v0
	v_mov_b32_e32 v45, v0
	v_mov_b32_e32 v58, v0
	v_mov_b32_e32 v59, v0
	v_mov_b32_e32 v60, v0
	v_mov_b32_e32 v61, v0
	v_mov_b32_e32 v12, v0
	v_mov_b32_e32 v13, v0
	v_mov_b32_e32 v14, v0
	v_mov_b32_e32 v15, v0
	v_mov_b32_e32 v28, v0
	v_mov_b32_e32 v29, v0
	v_mov_b32_e32 v30, v0
	v_mov_b32_e32 v31, v0
	v_mov_b32_e32 v46, v0
	v_mov_b32_e32 v47, v0
	v_mov_b32_e32 v48, v0
	v_mov_b32_e32 v49, v0
	v_mov_b32_e32 v86, v0
	v_mov_b32_e32 v87, v0
	v_mov_b32_e32 v88, v0
	v_mov_b32_e32 v89, v0
	v_readlane_b32 s13, v252, 41
	s_waitcnt vmcnt(5)
	ds_write_b128 v104, v[78:81] offset:36864
	s_waitcnt vmcnt(4)
	ds_write_b128 v104, v[82:85] offset:46080
	s_waitcnt vmcnt(3)
	ds_write_b128 v104, v[62:65]
	s_waitcnt vmcnt(2)
	ds_write_b128 v104, v[66:69] offset:9216
	s_waitcnt vmcnt(1)
	ds_write_b128 v104, v[70:73] offset:18432
	s_waitcnt vmcnt(0)
	ds_write_b128 v104, v[74:77] offset:27648
	s_waitcnt lgkmcnt(0)
	s_barrier
	v_lshl_add_u64 v[214:215], v[90:91], 0, v[32:33]
	v_add_co_u32_e32 v216, vcc, 0x1ed00000, v214
	v_lshl_add_u64 v[198:199], v[92:93], 0, v[32:33]
	s_nop 0
	v_addc_co_u32_e32 v217, vcc, 0, v215, vcc
	v_add_co_u32_e32 v218, vcc, 0x1ed40000, v214
	v_lshl_add_u64 v[202:203], v[94:95], 0, v[32:33]
	v_lshl_add_u64 v[206:207], v[96:97], 0, v[32:33]
	v_lshl_add_u64 v[210:211], v[98:99], 0, v[32:33]
	v_addc_co_u32_e32 v219, vcc, 0, v215, vcc
	global_load_dwordx4 v[198:201], v[198:199], off
	s_nop 0
	global_load_dwordx4 v[202:205], v[202:203], off
	s_nop 0
	global_load_dwordx4 v[206:209], v[206:207], off
	s_nop 0
	global_load_dwordx4 v[210:213], v[210:211], off
	s_nop 0
	global_load_dwordx4 v[214:217], v[216:217], off offset:128
	s_nop 0
	global_load_dwordx4 v[218:221], v[218:219], off offset:128
	s_mov_b64 s[0:1], 0x1200
	v_lshl_add_u64 v[90:91], v[90:91], 0, s[88:89]
	v_lshl_add_u64 v[92:93], v[92:93], 0, s[0:1]
	v_lshl_add_u64 v[94:95], v[94:95], 0, s[0:1]
	v_lshl_add_u64 v[96:97], v[96:97], 0, s[0:1]
	v_lshl_add_u64 v[98:99], v[98:99], 0, s[0:1]
	s_mov_b32 s6, 0
; DEVI f32x4 mfma16(bf16x8 a, bf16x8 b, f32x4 c) { return __builtin_amdgcn_mfma_f32_16x16x32_bf16(a, b, c, 0, 0, 0); }
; template <bool ROWSS, class AD, class Epi>
; DEVI void gemm_tile(const AD& ad, const bf16_t* __restrict__ Bt, int K, int m0, int n0, const Epi& epi, unsigned char* lds, int wv) {
;     ...
;   for (int kk = 0; kk < nk; ++kk) {
;     if (kk + 1 < nk) {
; #pragma unroll
;       for (int i = 0; i < 4; ++i) ra[i] = *(const u32x4*)(ap[i] + (size_t)(kk + 1) * aks);
; #pragma unroll
;       for (int i = 0; i < 2; ++i) rb[i] = *(const u32x4*)(bp[i] + (kk + 1) * 64);
;     }
;     const unsigned char* A = lds + (kk & 1) * LDS_STAGE + (wm * 64 + idx) * LDS_ROW + quad * 16;
;     const unsigned char* B = lds + (kk & 1) * LDS_STAGE + LDS_A_BYTES + (wn * 64 + idx) * LDS_ROW + quad * 16;
; #pragma unroll
;     for (int ks = 0; ks < 2; ++ks) {
;       bf16x8 af[4], wf[4];
; #pragma unroll
;       for (int i = 0; i < 4; ++i) af[i] = *(const bf16x8*)(A + i * 16 * LDS_ROW + ks * 64);
; #pragma unroll
;       for (int j = 0; j < 4; ++j) wf[j] = *(const bf16x8*)(B + j * 16 * LDS_ROW + ks * 64);
; #pragma unroll
;       for (int i = 0; i < 4; ++i)
; #pragma unroll
;         for (int j = 0; j < 4; ++j) acc[i][j] = mfma16(wf[j], af[i], acc[i][j]);
;     }
;     if (kk + 1 < nk) stage_write((kk + 1) & 1);
;     __syncthreads();
.Lc1k_loop:
	v_lshl_add_u64 v[78:79], v[90:91], 0, v[32:33]
	v_add_co_u32_e32 v80, vcc, 0x1ed00000, v78
	v_lshl_add_u64 v[62:63], v[92:93], 0, v[32:33]
	s_nop 0
	v_addc_co_u32_e32 v81, vcc, 0, v79, vcc
	v_add_co_u32_e32 v82, vcc, 0x1ed40000, v78
	v_lshl_add_u64 v[66:67], v[94:95], 0, v[32:33]
	v_lshl_add_u64 v[70:71], v[96:97], 0, v[32:33]
	v_lshl_add_u64 v[74:75], v[98:99], 0, v[32:33]
	v_addc_co_u32_e32 v83, vcc, 0, v79, vcc
	global_load_dwordx4 v[62:65], v[62:63], off
	s_nop 0
	global_load_dwordx4 v[66:69], v[66:67], off
	s_nop 0
	global_load_dwordx4 v[70:73], v[70:71], off
	s_nop 0
	global_load_dwordx4 v[74:77], v[74:75], off
	s_nop 0
	global_load_dwordx4 v[78:81], v[80:81], off offset:128
	s_nop 0
	global_load_dwordx4 v[82:85], v[82:83], off offset:128
	s_mov_b64 s[0:1], 0x1200
	v_lshl_add_u64 v[90:91], v[90:91], 0, s[88:89]
	v_lshl_add_u64 v[92:93], v[92:93], 0, s[0:1]
	v_lshl_add_u64 v[94:95], v[94:95], 0, s[0:1]
	v_lshl_add_u64 v[96:97], v[96:97], 0, s[0:1]
	v_lshl_add_u64 v[98:99], v[98:99], 0, s[0:1]
	s_mov_b32 s5, 0
	v_add3_u32 v128, s5, v107, v106
	ds_read_b128 v[108:111], v128 offset:36864
	ds_read_b128 v[116:119], v128 offset:39168
	ds_read_b128 v[120:123], v128 offset:41472
	ds_read_b128 v[124:127], v128 offset:43776
	v_add3_u32 v129, s5, v105, v106
	ds_read_b128 v[112:115], v129
	s_waitcnt lgkmcnt(0)
	v_mfma_f32_16x16x32_bf16 v[86:89], v[108:111], v[112:115], v[86:89]
	v_mfma_f32_16x16x32_bf16 v[46:49], v[116:119], v[112:115], v[46:49]
	v_mfma_f32_16x16x32_bf16 v[28:31], v[120:123], v[112:115], v[28:31]
	v_mfma_f32_16x16x32_bf16 v[12:15], v[124:127], v[112:115], v[12:15]
	ds_read_b128 v[112:115], v129 offset:2304
	s_waitcnt lgkmcnt(0)
	v_mfma_f32_16x16x32_bf16 v[58:61], v[108:111], v[112:115], v[58:61]
	v_mfma_f32_16x16x32_bf16 v[42:45], v[116:119], v[112:115], v[42:45]
	v_mfma_f32_16x16x32_bf16 v[24:27], v[120:123], v[112:115], v[24:27]
	v_mfma_f32_16x16x32_bf16 v[8:11], v[124:127], v[112:115], v[8:11]
	ds_read_b128 v[112:115], v129 offset:4608
	s_waitcnt lgkmcnt(0)
	v_mfma_f32_16x16x32_bf16 v[54:57], v[108:111], v[112:115], v[54:57]
	v_mfma_f32_16x16x32_bf16 v[38:41], v[116:119], v[112:115], v[38:41]
	v_mfma_f32_16x16x32_bf16 v[20:23], v[120:123], v[112:115], v[20:23]
	v_mfma_f32_16x16x32_bf16 v[4:7], v[124:127], v[112:115], v[4:7]
	ds_read_b128 v[112:115], v129 offset:6912
	s_waitcnt lgkmcnt(0)
	v_mfma_f32_16x16x32_bf16 v[50:53], v[108:111], v[112:115], v[50:53]
	ds_read_b128 v[108:111], v128 offset:36928
	v_mfma_f32_16x16x32_bf16 v[34:37], v[116:119], v[112:115], v[34:37]
	ds_read_b128 v[116:119], v128 offset:39232
	v_mfma_f32_16x16x32_bf16 v[16:19], v[120:123], v[112:115], v[16:19]
	ds_read_b128 v[120:123], v128 offset:41536
	v_mfma_f32_16x16x32_bf16 v[0:3], v[124:127], v[112:115], v[0:3]
	ds_read_b128 v[124:127], v128 offset:43840
	ds_read_b128 v[112:115], v129 offset:64
	s_waitcnt lgkmcnt(0)
	v_mfma_f32_16x16x32_bf16 v[86:89], v[108:111], v[112:115], v[86:89]
	v_mfma_f32_16x16x32_bf16 v[46:49], v[116:119], v[112:115], v[46:49]
	v_mfma_f32_16x16x32_bf16 v[28:31], v[120:123], v[112:115], v[28:31]
	v_mfma_f32_16x16x32_bf16 v[12:15], v[124:127], v[112:115], v[12:15]
	ds_read_b128 v[112:115], v129 offset:2368
	s_waitcnt lgkmcnt(0)
	v_mfma_f32_16x16x32_bf16 v[58:61], v[108:111], v[112:115], v[58:61]
	v_mfma_f32_16x16x32_bf16 v[42:45], v[116:119], v[112:115], v[42:45]
	v_mfma_f32_16x16x32_bf16 v[24:27], v[120:123], v[112:115], v[24:27]
	v_mfma_f32_16x16x32_bf16 v[8:11], v[124:127], v[112:115], v[8:11]
	ds_read_b128 v[112:115], v129 offset:4672
	s_waitcnt lgkmcnt(0)
	v_mfma_f32_16x16x32_bf16 v[54:57], v[108:111], v[112:115], v[54:57]
	v_mfma_f32_16x16x32_bf16 v[38:41], v[116:119], v[112:115], v[38:41]
	v_mfma_f32_16x16x32_bf16 v[20:23], v[120:123], v[112:115], v[20:23]
	v_mfma_f32_16x16x32_bf16 v[4:7], v[124:127], v[112:115], v[4:7]
	ds_read_b128 v[112:115], v129 offset:6976
	s_waitcnt lgkmcnt(0)
	v_mfma_f32_16x16x32_bf16 v[50:53], v[108:111], v[112:115], v[50:53]
	v_mfma_f32_16x16x32_bf16 v[34:37], v[116:119], v[112:115], v[34:37]
	v_mfma_f32_16x16x32_bf16 v[16:19], v[120:123], v[112:115], v[16:19]
	v_mfma_f32_16x16x32_bf16 v[0:3], v[124:127], v[112:115], v[0:3]
	s_mov_b32 s0, 0xd800
	v_add_u32_e32 v108, s0, v104
	s_waitcnt vmcnt(11)
	ds_write_b128 v108, v[198:201]
	s_waitcnt vmcnt(10)
	ds_write_b128 v108, v[202:205] offset:9216
	s_waitcnt vmcnt(9)
	ds_write_b128 v108, v[206:209] offset:18432
	s_waitcnt vmcnt(8)
	ds_write_b128 v108, v[210:213] offset:27648
	s_waitcnt vmcnt(7)
	ds_write_b128 v108, v[214:217] offset:36864
	s_waitcnt vmcnt(6)
	ds_write_b128 v108, v[218:221] offset:46080
	s_waitcnt lgkmcnt(0)
	s_barrier
; DEVI f32x4 mfma16(bf16x8 a, bf16x8 b, f32x4 c) { return __builtin_amdgcn_mfma_f32_16x16x32_bf16(a, b, c, 0, 0, 0); }
; template <bool ROWSS, class AD, class Epi>
; DEVI void gemm_tile(const AD& ad, const bf16_t* __restrict__ Bt, int K, int m0, int n0, const Epi& epi, unsigned char* lds, int wv) {
;     ...
;   for (int kk = 0; kk < nk; ++kk) {
;     if (kk + 1 < nk) {
; #pragma unroll
;       for (int i = 0; i < 4; ++i) ra[i] = *(const u32x4*)(ap[i] + (size_t)(kk + 1) * aks);
; #pragma unroll
;       for (int i = 0; i < 2; ++i) rb[i] = *(const u32x4*)(bp[i] + (kk + 1) * 64);
;     }
;     const unsigned char* A = lds + (kk & 1) * LDS_STAGE + (wm * 64 + idx) * LDS_ROW + quad * 16;
;     const unsigned char* B = lds + (kk & 1) * LDS_STAGE + LDS_A_BYTES + (wn * 64 + idx) * LDS_ROW + quad * 16;
; #pragma unroll
;     for (int ks = 0; ks < 2; ++ks) {
;       bf16x8 af[4], wf[4];
; #pragma unroll
;       for (int i = 0; i < 4; ++i) af[i] = *(const bf16x8*)(A + i * 16 * LDS_ROW + ks * 64);
; #pragma unroll
;       for (int j = 0; j < 4; ++j) wf[j] = *(const bf16x8*)(B + j * 16 * LDS_ROW + ks * 64);
; #pragma unroll
;       for (int i = 0; i < 4; ++i)
; #pragma unroll
;         for (int j = 0; j < 4; ++j) acc[i][j] = mfma16(wf[j], af[i], acc[i][j]);
;     }
;     if (kk + 1 < nk) stage_write((kk + 1) & 1);
;     __syncthreads();
	v_lshl_add_u64 v[214:215], v[90:91], 0, v[32:33]
	v_add_co_u32_e32 v216, vcc, 0x1ed00000, v214
	v_lshl_add_u64 v[198:199], v[92:93], 0, v[32:33]
	s_nop 0
	v_addc_co_u32_e32 v217, vcc, 0, v215, vcc
	v_add_co_u32_e32 v218, vcc, 0x1ed40000, v214
	v_lshl_add_u64 v[202:203], v[94:95], 0, v[32:33]
	v_lshl_add_u64 v[206:207], v[96:97], 0, v[32:33]
	v_lshl_add_u64 v[210:211], v[98:99], 0, v[32:33]
	v_addc_co_u32_e32 v219, vcc, 0, v215, vcc
	global_load_dwordx4 v[198:201], v[198:199], off
	s_nop 0
	global_load_dwordx4 v[202:205], v[202:203], off
	s_nop 0
	global_load_dwordx4 v[206:209], v[206:207], off
	s_nop 0
	global_load_dwordx4 v[210:213], v[210:211], off
	s_nop 0
	global_load_dwordx4 v[214:217], v[216:217], off offset:128
	s_nop 0
	global_load_dwordx4 v[218:221], v[218:219], off offset:128
	s_mov_b64 s[0:1], 0x1200
	v_lshl_add_u64 v[90:91], v[90:91], 0, s[88:89]
	v_lshl_add_u64 v[92:93], v[92:93], 0, s[0:1]
	v_lshl_add_u64 v[94:95], v[94:95], 0, s[0:1]
	v_lshl_add_u64 v[96:97], v[96:97], 0, s[0:1]
	v_lshl_add_u64 v[98:99], v[98:99], 0, s[0:1]
	s_mov_b32 s5, 0xd800
	v_add3_u32 v128, s5, v107, v106
	ds_read_b128 v[108:111], v128 offset:36864
	ds_read_b128 v[116:119], v128 offset:39168
	ds_read_b128 v[120:123], v128 offset:41472
	ds_read_b128 v[124:127], v128 offset:43776
	v_add3_u32 v129, s5, v105, v106
	ds_read_b128 v[112:115], v129
	s_waitcnt lgkmcnt(0)
	v_mfma_f32_16x16x32_bf16 v[86:89], v[108:111], v[112:115], v[86:89]
	v_mfma_f32_16x16x32_bf16 v[46:49], v[116:119], v[112:115], v[46:49]
	v_mfma_f32_16x16x32_bf16 v[28:31], v[120:123], v[112:115], v[28:31]
	v_mfma_f32_16x16x32_bf16 v[12:15], v[124:127], v[112:115], v[12:15]
	ds_read_b128 v[112:115], v129 offset:2304
	s_waitcnt lgkmcnt(0)
	v_mfma_f32_16x16x32_bf16 v[58:61], v[108:111], v[112:115], v[58:61]
	v_mfma_f32_16x16x32_bf16 v[42:45], v[116:119], v[112:115], v[42:45]
	v_mfma_f32_16x16x32_bf16 v[24:27], v[120:123], v[112:115], v[24:27]
	v_mfma_f32_16x16x32_bf16 v[8:11], v[124:127], v[112:115], v[8:11]
	ds_read_b128 v[112:115], v129 offset:4608
	s_waitcnt lgkmcnt(0)
	v_mfma_f32_16x16x32_bf16 v[54:57], v[108:111], v[112:115], v[54:57]
	v_mfma_f32_16x16x32_bf16 v[38:41], v[116:119], v[112:115], v[38:41]
	v_mfma_f32_16x16x32_bf16 v[20:23], v[120:123], v[112:115], v[20:23]
	v_mfma_f32_16x16x32_bf16 v[4:7], v[124:127], v[112:115], v[4:7]
	ds_read_b128 v[112:115], v129 offset:6912
	s_waitcnt lgkmcnt(0)
	v_mfma_f32_16x16x32_bf16 v[50:53], v[108:111], v[112:115], v[50:53]
	ds_read_b128 v[108:111], v128 offset:36928
	v_mfma_f32_16x16x32_bf16 v[34:37], v[116:119], v[112:115], v[34:37]
	ds_read_b128 v[116:119], v128 offset:39232
	v_mfma_f32_16x16x32_bf16 v[16:19], v[120:123], v[112:115], v[16:19]
	ds_read_b128 v[120:123], v128 offset:41536
	v_mfma_f32_16x16x32_bf16 v[0:3], v[124:127], v[112:115], v[0:3]
	ds_read_b128 v[124:127], v128 offset:43840
	ds_read_b128 v[112:115], v129 offset:64
	s_waitcnt lgkmcnt(0)
	v_mfma_f32_16x16x32_bf16 v[86:89], v[108:111], v[112:115], v[86:89]
	v_mfma_f32_16x16x32_bf16 v[46:49], v[116:119], v[112:115], v[46:49]
	v_mfma_f32_16x16x32_bf16 v[28:31], v[120:123], v[112:115], v[28:31]
	v_mfma_f32_16x16x32_bf16 v[12:15], v[124:127], v[112:115], v[12:15]
	ds_read_b128 v[112:115], v129 offset:2368
	s_waitcnt lgkmcnt(0)
	v_mfma_f32_16x16x32_bf16 v[58:61], v[108:111], v[112:115], v[58:61]
	v_mfma_f32_16x16x32_bf16 v[42:45], v[116:119], v[112:115], v[42:45]
	v_mfma_f32_16x16x32_bf16 v[24:27], v[120:123], v[112:115], v[24:27]
	v_mfma_f32_16x16x32_bf16 v[8:11], v[124:127], v[112:115], v[8:11]
	ds_read_b128 v[112:115], v129 offset:4672
	s_waitcnt lgkmcnt(0)
	v_mfma_f32_16x16x32_bf16 v[54:57], v[108:111], v[112:115], v[54:57]
	v_mfma_f32_16x16x32_bf16 v[38:41], v[116:119], v[112:115], v[38:41]
	v_mfma_f32_16x16x32_bf16 v[20:23], v[120:123], v[112:115], v[20:23]
	v_mfma_f32_16x16x32_bf16 v[4:7], v[124:127], v[112:115], v[4:7]
	ds_read_b128 v[112:115], v129 offset:6976
	s_waitcnt lgkmcnt(0)
	v_mfma_f32_16x16x32_bf16 v[50:53], v[108:111], v[112:115], v[50:53]
	v_mfma_f32_16x16x32_bf16 v[34:37], v[116:119], v[112:115], v[34:37]
	v_mfma_f32_16x16x32_bf16 v[16:19], v[120:123], v[112:115], v[16:19]
	v_mfma_f32_16x16x32_bf16 v[0:3], v[124:127], v[112:115], v[0:3]
	s_mov_b32 s0, 0
	v_add_u32_e32 v108, s0, v104
	s_waitcnt vmcnt(11)
	ds_write_b128 v108, v[62:65]
	s_waitcnt vmcnt(10)
	ds_write_b128 v108, v[66:69] offset:9216
	s_waitcnt vmcnt(9)
	ds_write_b128 v108, v[70:73] offset:18432
	s_waitcnt vmcnt(8)
	ds_write_b128 v108, v[74:77] offset:27648
	s_waitcnt vmcnt(7)
	ds_write_b128 v108, v[78:81] offset:36864
	s_waitcnt vmcnt(6)
	ds_write_b128 v108, v[82:85] offset:46080
	s_waitcnt lgkmcnt(0)
	s_barrier
	s_add_i32 s6, s6, 1
	s_cmp_lg_u32 s6, 15
	s_cbranch_scc1 .Lc1k_loop
; DEVI f32x4 mfma16(bf16x8 a, bf16x8 b, f32x4 c) { return __builtin_amdgcn_mfma_f32_16x16x32_bf16(a, b, c, 0, 0, 0); }
; template <bool ROWSS, class AD, class Epi>
; DEVI void gemm_tile(const AD& ad, const bf16_t* __restrict__ Bt, int K, int m0, int n0, const Epi& epi, unsigned char* lds, int wv) {
;     ...
;   for (int kk = 0; kk < nk; ++kk) {
;     if (kk + 1 < nk) {
; #pragma unroll
;       for (int i = 0; i < 4; ++i) ra[i] = *(const u32x4*)(ap[i] + (size_t)(kk + 1) * aks);
; #pragma unroll
;       for (int i = 0; i < 2; ++i) rb[i] = *(const u32x4*)(bp[i] + (kk + 1) * 64);
;     }
;     const unsigned char* A = lds + (kk & 1) * LDS_STAGE + (wm * 64 + idx) * LDS_ROW + quad * 16;
;     const unsigned char* B = lds + (kk & 1) * LDS_STAGE + LDS_A_BYTES + (wn * 64 + idx) * LDS_ROW + quad * 16;
; #pragma unroll
;     for (int ks = 0; ks < 2; ++ks) {
;       bf16x8 af[4], wf[4];
; #pragma unroll
;       for (int i = 0; i < 4; ++i) af[i] = *(const bf16x8*)(A + i * 16 * LDS_ROW + ks * 64);
; #pragma unroll
;       for (int j = 0; j < 4; ++j) wf[j] = *(const bf16x8*)(B + j * 16 * LDS_ROW + ks * 64);
; #pragma unroll
;       for (int i = 0; i < 4; ++i)
; #pragma unroll
;         for (int j = 0; j < 4; ++j) acc[i][j] = mfma16(wf[j], af[i], acc[i][j]);
;     }
;     if (kk + 1 < nk) stage_write((kk + 1) & 1);
;     __syncthreads();
	s_mov_b32 s5, 0
	v_add3_u32 v128, s5, v107, v106
	ds_read_b128 v[108:111], v128 offset:36864
	ds_read_b128 v[116:119], v128 offset:39168
	ds_read_b128 v[120:123], v128 offset:41472
	ds_read_b128 v[124:127], v128 offset:43776
	v_add3_u32 v129, s5, v105, v106
	ds_read_b128 v[112:115], v129
	s_waitcnt lgkmcnt(0)
	v_mfma_f32_16x16x32_bf16 v[86:89], v[108:111], v[112:115], v[86:89]
	v_mfma_f32_16x16x32_bf16 v[46:49], v[116:119], v[112:115], v[46:49]
	v_mfma_f32_16x16x32_bf16 v[28:31], v[120:123], v[112:115], v[28:31]
	v_mfma_f32_16x16x32_bf16 v[12:15], v[124:127], v[112:115], v[12:15]
	ds_read_b128 v[112:115], v129 offset:2304
	s_waitcnt lgkmcnt(0)
	v_mfma_f32_16x16x32_bf16 v[58:61], v[108:111], v[112:115], v[58:61]
	v_mfma_f32_16x16x32_bf16 v[42:45], v[116:119], v[112:115], v[42:45]
	v_mfma_f32_16x16x32_bf16 v[24:27], v[120:123], v[112:115], v[24:27]
	v_mfma_f32_16x16x32_bf16 v[8:11], v[124:127], v[112:115], v[8:11]
	ds_read_b128 v[112:115], v129 offset:4608
	s_waitcnt lgkmcnt(0)
	v_mfma_f32_16x16x32_bf16 v[54:57], v[108:111], v[112:115], v[54:57]
	v_mfma_f32_16x16x32_bf16 v[38:41], v[116:119], v[112:115], v[38:41]
	v_mfma_f32_16x16x32_bf16 v[20:23], v[120:123], v[112:115], v[20:23]
	v_mfma_f32_16x16x32_bf16 v[4:7], v[124:127], v[112:115], v[4:7]
	ds_read_b128 v[112:115], v129 offset:6912
	s_waitcnt lgkmcnt(0)
	v_mfma_f32_16x16x32_bf16 v[50:53], v[108:111], v[112:115], v[50:53]
	ds_read_b128 v[108:111], v128 offset:36928
	v_mfma_f32_16x16x32_bf16 v[34:37], v[116:119], v[112:115], v[34:37]
	ds_read_b128 v[116:119], v128 offset:39232
	v_mfma_f32_16x16x32_bf16 v[16:19], v[120:123], v[112:115], v[16:19]
	ds_read_b128 v[120:123], v128 offset:41536
	v_mfma_f32_16x16x32_bf16 v[0:3], v[124:127], v[112:115], v[0:3]
	ds_read_b128 v[124:127], v128 offset:43840
	ds_read_b128 v[112:115], v129 offset:64
	s_waitcnt lgkmcnt(0)
	v_mfma_f32_16x16x32_bf16 v[86:89], v[108:111], v[112:115], v[86:89]
	v_mfma_f32_16x16x32_bf16 v[46:49], v[116:119], v[112:115], v[46:49]
	v_mfma_f32_16x16x32_bf16 v[28:31], v[120:123], v[112:115], v[28:31]
	v_mfma_f32_16x16x32_bf16 v[12:15], v[124:127], v[112:115], v[12:15]
	ds_read_b128 v[112:115], v129 offset:2368
	s_waitcnt lgkmcnt(0)
	v_mfma_f32_16x16x32_bf16 v[58:61], v[108:111], v[112:115], v[58:61]
	v_mfma_f32_16x16x32_bf16 v[42:45], v[116:119], v[112:115], v[42:45]
	v_mfma_f32_16x16x32_bf16 v[24:27], v[120:123], v[112:115], v[24:27]
	v_mfma_f32_16x16x32_bf16 v[8:11], v[124:127], v[112:115], v[8:11]
	ds_read_b128 v[112:115], v129 offset:4672
	s_waitcnt lgkmcnt(0)
	v_mfma_f32_16x16x32_bf16 v[54:57], v[108:111], v[112:115], v[54:57]
	v_mfma_f32_16x16x32_bf16 v[38:41], v[116:119], v[112:115], v[38:41]
	v_mfma_f32_16x16x32_bf16 v[20:23], v[120:123], v[112:115], v[20:23]
	v_mfma_f32_16x16x32_bf16 v[4:7], v[124:127], v[112:115], v[4:7]
	ds_read_b128 v[112:115], v129 offset:6976
	s_waitcnt lgkmcnt(0)
	v_mfma_f32_16x16x32_bf16 v[50:53], v[108:111], v[112:115], v[50:53]
	v_mfma_f32_16x16x32_bf16 v[34:37], v[116:119], v[112:115], v[34:37]
	v_mfma_f32_16x16x32_bf16 v[16:19], v[120:123], v[112:115], v[16:19]
	v_mfma_f32_16x16x32_bf16 v[0:3], v[124:127], v[112:115], v[0:3]
	s_mov_b32 s0, 0xd800
	v_add_u32_e32 v108, s0, v104
	s_waitcnt vmcnt(5)
	ds_write_b128 v108, v[198:201]
	s_waitcnt vmcnt(4)
	ds_write_b128 v108, v[202:205] offset:9216
	s_waitcnt vmcnt(3)
	ds_write_b128 v108, v[206:209] offset:18432
	s_waitcnt vmcnt(2)
	ds_write_b128 v108, v[210:213] offset:27648
	s_waitcnt vmcnt(1)
	ds_write_b128 v108, v[214:217] offset:36864
	s_waitcnt vmcnt(0)
	ds_write_b128 v108, v[218:221] offset:46080
	s_waitcnt lgkmcnt(0)
	s_barrier
	s_mov_b32 s5, 0xd800
	v_add3_u32 v128, s5, v107, v106
	ds_read_b128 v[108:111], v128 offset:36864
	ds_read_b128 v[116:119], v128 offset:39168
	ds_read_b128 v[120:123], v128 offset:41472
	ds_read_b128 v[124:127], v128 offset:43776
	v_add3_u32 v129, s5, v105, v106
	ds_read_b128 v[112:115], v129
	s_waitcnt lgkmcnt(0)
	v_mfma_f32_16x16x32_bf16 v[86:89], v[108:111], v[112:115], v[86:89]
	v_mfma_f32_16x16x32_bf16 v[46:49], v[116:119], v[112:115], v[46:49]
	v_mfma_f32_16x16x32_bf16 v[28:31], v[120:123], v[112:115], v[28:31]
	v_mfma_f32_16x16x32_bf16 v[12:15], v[124:127], v[112:115], v[12:15]
	ds_read_b128 v[112:115], v129 offset:2304
	s_waitcnt lgkmcnt(0)
	v_mfma_f32_16x16x32_bf16 v[58:61], v[108:111], v[112:115], v[58:61]
	v_mfma_f32_16x16x32_bf16 v[42:45], v[116:119], v[112:115], v[42:45]
	v_mfma_f32_16x16x32_bf16 v[24:27], v[120:123], v[112:115], v[24:27]
	v_mfma_f32_16x16x32_bf16 v[8:11], v[124:127], v[112:115], v[8:11]
	ds_read_b128 v[112:115], v129 offset:4608
	s_waitcnt lgkmcnt(0)
	v_mfma_f32_16x16x32_bf16 v[54:57], v[108:111], v[112:115], v[54:57]
	v_mfma_f32_16x16x32_bf16 v[38:41], v[116:119], v[112:115], v[38:41]
	v_mfma_f32_16x16x32_bf16 v[20:23], v[120:123], v[112:115], v[20:23]
	v_mfma_f32_16x16x32_bf16 v[4:7], v[124:127], v[112:115], v[4:7]
	ds_read_b128 v[112:115], v129 offset:6912
	s_waitcnt lgkmcnt(0)
	v_mfma_f32_16x16x32_bf16 v[50:53], v[108:111], v[112:115], v[50:53]
	ds_read_b128 v[108:111], v128 offset:36928
	v_mfma_f32_16x16x32_bf16 v[34:37], v[116:119], v[112:115], v[34:37]
	ds_read_b128 v[116:119], v128 offset:39232
	v_mfma_f32_16x16x32_bf16 v[16:19], v[120:123], v[112:115], v[16:19]
	ds_read_b128 v[120:123], v128 offset:41536
	v_mfma_f32_16x16x32_bf16 v[0:3], v[124:127], v[112:115], v[0:3]
	ds_read_b128 v[124:127], v128 offset:43840
	ds_read_b128 v[112:115], v129 offset:64
	s_waitcnt lgkmcnt(0)
	v_mfma_f32_16x16x32_bf16 v[86:89], v[108:111], v[112:115], v[86:89]
	v_mfma_f32_16x16x32_bf16 v[46:49], v[116:119], v[112:115], v[46:49]
	v_mfma_f32_16x16x32_bf16 v[28:31], v[120:123], v[112:115], v[28:31]
	v_mfma_f32_16x16x32_bf16 v[12:15], v[124:127], v[112:115], v[12:15]
	ds_read_b128 v[112:115], v129 offset:2368
	s_waitcnt lgkmcnt(0)
	v_mfma_f32_16x16x32_bf16 v[58:61], v[108:111], v[112:115], v[58:61]
	v_mfma_f32_16x16x32_bf16 v[42:45], v[116:119], v[112:115], v[42:45]
	v_mfma_f32_16x16x32_bf16 v[24:27], v[120:123], v[112:115], v[24:27]
	v_mfma_f32_16x16x32_bf16 v[8:11], v[124:127], v[112:115], v[8:11]
	ds_read_b128 v[112:115], v129 offset:4672
	s_waitcnt lgkmcnt(0)
	v_mfma_f32_16x16x32_bf16 v[54:57], v[108:111], v[112:115], v[54:57]
	v_mfma_f32_16x16x32_bf16 v[38:41], v[116:119], v[112:115], v[38:41]
	v_mfma_f32_16x16x32_bf16 v[20:23], v[120:123], v[112:115], v[20:23]
	v_mfma_f32_16x16x32_bf16 v[4:7], v[124:127], v[112:115], v[4:7]
	ds_read_b128 v[112:115], v129 offset:6976
	s_waitcnt lgkmcnt(0)
	v_mfma_f32_16x16x32_bf16 v[50:53], v[108:111], v[112:115], v[50:53]
	v_mfma_f32_16x16x32_bf16 v[34:37], v[116:119], v[112:115], v[34:37]
	v_mfma_f32_16x16x32_bf16 v[16:19], v[120:123], v[112:115], v[16:19]
	v_mfma_f32_16x16x32_bf16 v[0:3], v[124:127], v[112:115], v[0:3]
	s_waitcnt lgkmcnt(0)
	s_barrier
